# gate GEMM column-to-tile map changed so each workgroup writes whole 128-byte lines of the gate-ratio buffer (weight row permutation + epilogue channel offset)
# baseline (speedup 1.0000x reference)
.LBB0_892:
	s_load_dwordx2 s[98:99], s[88:89], 0x150
	s_waitcnt lgkmcnt(0)
	s_add_u32 s98, s98, 0x400000
	s_addc_u32 s99, s99, 0
	v_or_b32_e32 v20, s10, v26
	v_mad_u64_u32 v[16:17], s[6:7], v20, s27, v[16:17]
	global_load_dwordx4 v[32:35], v[16:17], off
	v_add_u32_e32 v20, 0x14a0, v31
	s_and_b32 s6, 0xffff, s31
	v_add_u32_e32 v36, 0x14a8, v31
	s_lshl_b32 s10, s10, 1
	s_lshr_b32 s31, s6, 4
	v_lshl_add_u64 v[40:41], v[2:3], 0, s[10:11]
	s_lshr_b32 s7, s6, 6
	s_lshl_b32 s10, s6, 2
	s_and_b32 s6, s6, 0x60
	s_and_b32 s31, s31, 0x80
	s_and_b32 s7, s7, 16
	s_or_b32 s33, s31, s6
	s_and_b32 s10, s10, 0xe00
	s_or_b32 s33, s33, s7
	s_or_b32 s33, s33, s10
	v_mov_b32_e32 v37, v1
	v_mov_b32_e32 v43, v1
	s_waitcnt vmcnt(0)
	v_pk_mul_f32 v[32:33], v[32:33], v[18:19] op_sel_hi:[1,0]
	v_pk_mul_f32 v[16:17], v[34:35], v[18:19] op_sel_hi:[1,0]
	ds_write2_b32 v20, v32, v33 offset1:1
	ds_write2_b32 v36, v16, v17 offset1:1
	s_waitcnt lgkmcnt(0)
	ds_read2_b32 v[16:17], v27 offset1:33
	s_waitcnt lgkmcnt(0)
	v_cvt_pk_bf16_f32 v32, v16, v17
	ds_read2_b32 v[16:17], v27 offset0:66 offset1:99
	s_waitcnt lgkmcnt(0)
	v_cvt_pk_bf16_f32 v33, v16, v17
	ds_read2_b32 v[16:17], v27 offset0:132 offset1:165
	v_or_b32_e32 v18, s33, v9
	s_waitcnt lgkmcnt(0)
	v_cvt_pk_bf16_f32 v34, v16, v17
	ds_read2_b32 v[16:17], v27 offset0:198 offset1:231
	v_lshlrev_b32_e32 v36, 11, v18
	s_waitcnt lgkmcnt(0)
	v_cvt_pk_bf16_f32 v35, v16, v17
	ds_read2_b32 v[16:17], v27 offset0:8 offset1:41
	v_lshl_add_u64 v[36:37], v[40:41], 0, v[36:37]
	v_mov_b32_e32 v194, s98
	v_sub_u32_e32 v190, v36, v194
	v_bfe_u32 v191, v190, 19, 1
	v_bfe_u32 v192, v190, 17, 1
	v_bfe_u32 v193, v190, 16, 1
	v_and_b32_e32 v190, 0xfff4ffff, v190
	v_lshl_or_b32 v190, v192, 19, v190
	v_lshl_or_b32 v190, v193, 17, v190
	v_lshl_or_b32 v190, v191, 16, v190
	v_mov_b32_e32 v195, 0
	v_mov_b32_e32 v196, v190
	v_mov_b32_e32 v197, 0
	v_lshl_add_u64 v[196:197], v[196:197], 0, s[98:99]
	global_store_dwordx4 v[196:197], v[32:35], off
	v_or_b32_e32 v18, s33, v19
	v_lshlrev_b32_e32 v42, 11, v18
	s_waitcnt lgkmcnt(0)
	v_cvt_pk_bf16_f32 v32, v16, v17
	ds_read2_b32 v[16:17], v27 offset0:74 offset1:107
	s_waitcnt lgkmcnt(0)
	v_cvt_pk_bf16_f32 v33, v16, v17
	ds_read2_b32 v[16:17], v27 offset0:140 offset1:173
	s_waitcnt lgkmcnt(0)
	v_cvt_pk_bf16_f32 v34, v16, v17
	ds_read2_b32 v[16:17], v27 offset0:206 offset1:239
	v_or_b32_e32 v18, s6, v28
	s_waitcnt lgkmcnt(0)
	v_cvt_pk_bf16_f32 v35, v16, v17
	ds_read2_b32 v[16:17], v27 offset0:16 offset1:49
	v_lshl_add_u64 v[42:43], v[40:41], 0, v[42:43]
	v_or_b32_e32 v18, s31, v18
	v_mov_b32_e32 v194, s98
	v_sub_u32_e32 v190, v42, v194
	v_bfe_u32 v191, v190, 19, 1
	v_bfe_u32 v192, v190, 17, 1
	v_bfe_u32 v193, v190, 16, 1
	v_and_b32_e32 v190, 0xfff4ffff, v190
	v_lshl_or_b32 v190, v192, 19, v190
	v_lshl_or_b32 v190, v193, 17, v190
	v_lshl_or_b32 v190, v191, 16, v190
	v_mov_b32_e32 v195, 0
	v_mov_b32_e32 v196, v190
	v_mov_b32_e32 v197, 0
	v_lshl_add_u64 v[196:197], v[196:197], 0, s[98:99]
	global_store_dwordx4 v[196:197], v[32:35], off
	v_add_co_u32_e32 v36, vcc, s28, v36
	s_waitcnt lgkmcnt(0)
	v_cvt_pk_bf16_f32 v32, v16, v17
	ds_read2_b32 v[16:17], v27 offset0:82 offset1:115
	v_or_b32_e32 v18, s7, v18
	s_waitcnt lgkmcnt(0)
	v_cvt_pk_bf16_f32 v33, v16, v17
	ds_read2_b32 v[16:17], v27 offset0:148 offset1:181
	v_addc_co_u32_e32 v37, vcc, 0, v37, vcc
	v_or_b32_e32 v18, s10, v18
	s_waitcnt lgkmcnt(0)
	v_cvt_pk_bf16_f32 v34, v16, v17
	ds_read2_b32 v[16:17], v27 offset0:214 offset1:247
	s_waitcnt lgkmcnt(0)
	v_cvt_pk_bf16_f32 v35, v16, v17
	v_mov_b32_e32 v194, s98
	v_sub_u32_e32 v190, v36, v194
	v_bfe_u32 v191, v190, 19, 1
	v_bfe_u32 v192, v190, 17, 1
	v_bfe_u32 v193, v190, 16, 1
	v_and_b32_e32 v190, 0xfff4ffff, v190
	v_lshl_or_b32 v190, v192, 19, v190
	v_lshl_or_b32 v190, v193, 17, v190
	v_lshl_or_b32 v190, v191, 16, v190
	v_mov_b32_e32 v195, 0
	v_mov_b32_e32 v196, v190
	v_mov_b32_e32 v197, 0
	v_lshl_add_u64 v[196:197], v[196:197], 0, s[98:99]
	global_store_dwordx4 v[196:197], v[32:35], off
	v_mov_b32_e32 v37, v1
	v_lshlrev_b32_e32 v36, 11, v18
	ds_read2_b32 v[16:17], v27 offset0:24 offset1:57
	v_lshl_add_u64 v[36:37], v[40:41], 0, v[36:37]
	s_waitcnt lgkmcnt(0)
	v_cvt_pk_bf16_f32 v32, v16, v17
	ds_read2_b32 v[16:17], v27 offset0:90 offset1:123
	v_add_co_u32_e32 v36, vcc, 0x80000, v36
	s_waitcnt lgkmcnt(0)
	v_cvt_pk_bf16_f32 v33, v16, v17
	ds_read2_b32 v[16:17], v27 offset0:156 offset1:189
	v_addc_co_u32_e32 v37, vcc, 0, v37, vcc
	s_waitcnt lgkmcnt(0)
	v_cvt_pk_bf16_f32 v34, v16, v17
	ds_read2_b32 v[16:17], v27 offset0:222 offset1:255
	s_waitcnt lgkmcnt(0)
	v_cvt_pk_bf16_f32 v35, v16, v17
	v_mov_b32_e32 v194, s98
	v_sub_u32_e32 v190, v36, v194
	v_bfe_u32 v191, v190, 19, 1
	v_bfe_u32 v192, v190, 17, 1
	v_bfe_u32 v193, v190, 16, 1
	v_and_b32_e32 v190, 0xfff4ffff, v190
	v_lshl_or_b32 v190, v192, 19, v190
	v_lshl_or_b32 v190, v193, 17, v190
	v_lshl_or_b32 v190, v191, 16, v190
	v_mov_b32_e32 v195, 0
	v_mov_b32_e32 v196, v190
	v_mov_b32_e32 v197, 0
	v_lshl_add_u64 v[196:197], v[196:197], 0, s[98:99]
	global_store_dwordx4 v[196:197], v[32:35], off
	s_waitcnt lgkmcnt(0)
	s_and_b32 s31, s2, 0xfffffe00
	s_cmpk_lt_i32 s31, 0xa00
	s_mov_b64 s[6:7], -1
	s_cbranch_scc0 .LBB0_885

.LBB0_1224:
	v_lshl_add_u32 v156, s6, 8, v158
	v_mov_b64_e32 v[200:201], s[22:23]
	v_ashrrev_i32_e32 v157, 31, v156
	v_add_u32_e32 v154, 16, v156
	v_lshlrev_b64 v[142:143], 6, v[156:157]
	v_ashrrev_i32_e32 v155, 31, v154
	v_lshl_add_u64 v[142:143], v[132:133], 0, v[142:143]
	v_lshlrev_b64 v[144:145], 6, v[154:155]
	v_lshl_add_u64 v[144:145], v[132:133], 0, v[144:145]
	global_load_dwordx4 v[168:171], v[142:143], off
	global_load_dwordx4 v[172:175], v[144:145], off
	v_add_u32_e32 v152, 32, v156
	v_ashrrev_i32_e32 v153, 31, v152
	v_add_u32_e32 v150, 48, v156
	v_lshlrev_b64 v[142:143], 6, v[152:153]
	v_ashrrev_i32_e32 v151, 31, v150
	v_lshl_add_u64 v[142:143], v[132:133], 0, v[142:143]
	v_lshlrev_b64 v[144:145], 6, v[150:151]
	v_lshl_add_u64 v[144:145], v[132:133], 0, v[144:145]
	global_load_dwordx4 v[176:179], v[142:143], off
	global_load_dwordx4 v[180:183], v[144:145], off
	v_add_u32_e32 v148, 0x80, v156
	v_ashrrev_i32_e32 v149, 31, v148
	v_lshlrev_b64 v[142:143], 6, v[148:149]
	v_add_u32_e32 v146, 0x90, v156
	v_lshl_add_u64 v[142:143], v[132:133], 0, v[142:143]
	v_ashrrev_i32_e32 v147, 31, v146
	global_load_dwordx4 v[184:187], v[142:143], off
	v_lshlrev_b64 v[142:143], 6, v[146:147]
	v_lshl_add_u64 v[142:143], v[132:133], 0, v[142:143]
	global_load_dwordx4 v[188:191], v[142:143], off
	v_add_u32_e32 v144, 0xa0, v156
	v_add_u32_e32 v142, 0xb0, v156
	v_ashrrev_i32_e32 v145, 31, v144
	v_ashrrev_i32_e32 v143, 31, v142
	v_lshlrev_b64 v[192:193], 6, v[144:145]
	v_lshlrev_b64 v[194:195], 6, v[142:143]
	v_lshl_add_u64 v[192:193], v[132:133], 0, v[192:193]
	v_lshl_add_u64 v[196:197], v[132:133], 0, v[194:195]
	global_load_dwordx4 v[192:195], v[192:193], off
	s_nop 0
	global_load_dwordx4 v[196:199], v[196:197], off
	v_lshlrev_b64 v[156:157], 13, v[156:157]
	s_waitcnt vmcnt(0)
	v_mov_b32_e32 v202, v169
	v_mov_b32_e32 v203, v170
	v_mov_b32_e32 v169, v171
	v_mov_b32_e32 v170, v173
	v_mov_b32_e32 v171, v174
	v_mov_b32_e32 v173, v175
	v_pk_add_f32 v[168:169], v[202:203], v[168:169]
	v_pk_add_f32 v[170:171], v[170:171], v[172:173]
	v_mov_b32_e32 v173, v168
	v_mov_b32_e32 v172, v170
	v_mov_b32_e32 v168, v171
	v_pk_add_f32 v[168:169], v[172:173], v[168:169]
	v_mov_b32_e32 v174, v177
	v_mov_b32_e32 v175, v178
	v_mov_b32_e32 v177, v179
	v_mov_b32_e32 v178, v181
	v_mov_b32_e32 v179, v182
	v_mov_b32_e32 v181, v183
	ds_bpermute_b32 v173, v160, v169
	ds_bpermute_b32 v172, v160, v168
	v_pk_add_f32 v[174:175], v[174:175], v[176:177]
	v_pk_add_f32 v[176:177], v[178:179], v[180:181]
	v_mov_b32_e32 v171, v174
	v_mov_b32_e32 v170, v176
	v_mov_b32_e32 v174, v177
	v_pk_add_f32 v[170:171], v[170:171], v[174:175]
	ds_bpermute_b32 v175, v160, v171
	ds_bpermute_b32 v174, v160, v170
	s_waitcnt lgkmcnt(2)
	v_pk_add_f32 v[168:169], v[168:169], v[172:173]
	ds_bpermute_b32 v173, v161, v169
	ds_bpermute_b32 v172, v161, v168
	v_mov_b32_e32 v182, v185
	s_waitcnt lgkmcnt(2)
	v_pk_add_f32 v[170:171], v[170:171], v[174:175]
	ds_bpermute_b32 v175, v161, v171
	ds_bpermute_b32 v174, v161, v170
	v_mov_b32_e32 v183, v186
	v_mov_b32_e32 v185, v187
	v_mov_b32_e32 v186, v189
	v_mov_b32_e32 v187, v190
	v_mov_b32_e32 v189, v191
	s_waitcnt lgkmcnt(2)
	v_pk_add_f32 v[168:169], v[168:169], v[172:173]
	v_pk_add_f32 v[178:179], v[182:183], v[184:185]
	v_pk_add_f32 v[180:181], v[186:187], v[188:189]
	v_pk_fma_f32 v[168:169], v[168:169], s[20:21], v[200:201] op_sel_hi:[1,0,0]
	v_mov_b32_e32 v176, v180
	v_mov_b32_e32 v177, v178
	v_mov_b32_e32 v178, v181
	v_mul_f32_e32 v167, 0x4b800000, v169
	v_cmp_gt_f32_e32 vcc, s54, v169
	v_pk_add_f32 v[176:177], v[176:177], v[178:179]
	ds_bpermute_b32 v179, v160, v177
	v_cndmask_b32_e32 v167, v169, v167, vcc
	ds_bpermute_b32 v178, v160, v176
	s_waitcnt lgkmcnt(2)
	v_pk_add_f32 v[170:171], v[170:171], v[174:175]
	v_rsq_f32_e32 v167, v167
	v_pk_fma_f32 v[170:171], v[170:171], s[20:21], v[200:201] op_sel_hi:[1,0,0]
	v_mul_f32_e32 v172, 0x4b800000, v168
	v_cmp_gt_f32_e64 s[6:7], s54, v168
	v_mul_f32_e32 v173, 0x4b800000, v171
	v_cmp_gt_f32_e64 s[8:9], s54, v171
	v_cndmask_b32_e64 v168, v168, v172, s[6:7]
	v_rsq_f32_e32 v172, v168
	v_cndmask_b32_e64 v168, v171, v173, s[8:9]
	v_rsq_f32_e32 v173, v168
	v_mul_f32_e32 v168, 0x45800000, v167
	v_mul_f32_e32 v174, 0x4b800000, v170
	v_cndmask_b32_e32 v180, v167, v168, vcc
	v_cmp_gt_f32_e32 vcc, s54, v170
	s_waitcnt lgkmcnt(0)
	v_pk_add_f32 v[168:169], v[176:177], v[178:179]
	ds_bpermute_b32 v171, v161, v169
	v_cndmask_b32_e32 v167, v170, v174, vcc
	ds_bpermute_b32 v170, v161, v168
	v_mul_f32_e32 v175, 0x45800000, v172
	v_cndmask_b32_e64 v176, v172, v175, s[6:7]
	v_mul_f32_e32 v172, 0x45800000, v173
	v_cndmask_b32_e64 v177, v173, v172, s[8:9]
	s_waitcnt lgkmcnt(0)
	v_pk_add_f32 v[168:169], v[168:169], v[170:171]
	v_mov_b32_e32 v171, v194
	v_pk_fma_f32 v[168:169], v[168:169], s[20:21], v[200:201] op_sel_hi:[1,0,0]
	v_mov_b32_e32 v172, v197
	v_mul_f32_e32 v170, 0x4b800000, v169
	v_cmp_gt_f32_e64 s[6:7], s54, v169
	v_mov_b32_e32 v173, v198
	v_mov_b32_e32 v197, v199
	v_cndmask_b32_e64 v169, v169, v170, s[6:7]
	v_mov_b32_e32 v170, v193
	v_mov_b32_e32 v193, v195
	v_pk_add_f32 v[170:171], v[170:171], v[192:193]
	v_pk_add_f32 v[172:173], v[172:173], v[196:197]
	v_mov_b32_e32 v175, v170
	v_mov_b32_e32 v174, v172
	v_mov_b32_e32 v170, v173
	v_pk_add_f32 v[170:171], v[174:175], v[170:171]
	ds_bpermute_b32 v173, v160, v171
	ds_bpermute_b32 v172, v160, v170
	v_rsq_f32_e32 v179, v169
	v_mul_f32_e32 v169, 0x4b800000, v168
	v_cmp_gt_f32_e64 s[8:9], s54, v168
	v_rsq_f32_e32 v167, v167
	v_mul_f32_e32 v124, v124, v180
	v_cndmask_b32_e64 v168, v168, v169, s[8:9]
	v_rsq_f32_e32 v174, v168
	s_waitcnt lgkmcnt(0)
	v_pk_add_f32 v[168:169], v[170:171], v[172:173]
	ds_bpermute_b32 v173, v161, v169
	ds_bpermute_b32 v172, v161, v168
	v_med3_f32 v124, v124, s55, v166
	v_mul_f32_e32 v124, 0xbfb8aa3b, v124
	v_mul_f32_e32 v178, 0x45800000, v167
	v_exp_f32_e32 v124, v124
	s_waitcnt lgkmcnt(0)
	v_pk_add_f32 v[168:169], v[168:169], v[172:173]
	v_mul_f32_e32 v125, v125, v180
	v_pk_fma_f32 v[168:169], v[168:169], s[20:21], v[200:201] op_sel_hi:[1,0,0]
	v_cndmask_b32_e32 v171, v167, v178, vcc
	v_mul_f32_e32 v172, 0x4b800000, v169
	v_cmp_gt_f32_e32 vcc, s54, v169
	v_med3_f32 v125, v125, s55, v166
	v_mul_f32_e32 v112, v112, v180
	v_mul_f32_e32 v167, 0x45800000, v179
	v_cndmask_b32_e32 v169, v169, v172, vcc
	v_mul_f32_e32 v125, 0xbfb8aa3b, v125
	v_med3_f32 v112, v112, s55, v166
	v_cndmask_b32_e64 v170, v179, v167, s[6:7]
	v_mul_f32_e32 v167, 0x45800000, v174
	v_rsq_f32_e32 v172, v169
	v_mul_f32_e32 v169, 0x4b800000, v168
	v_cmp_gt_f32_e64 s[6:7], s54, v168
	v_exp_f32_e32 v125, v125
	v_mul_f32_e32 v112, 0xbfb8aa3b, v112
	v_cndmask_b32_e64 v168, v168, v169, s[6:7]
	v_cndmask_b32_e64 v169, v174, v167, s[8:9]
	v_add_f32_e32 v174, 1.0, v124
	v_exp_f32_e32 v124, v112
	v_mul_f32_e32 v112, v113, v180
	v_med3_f32 v112, v112, s55, v166
	v_mul_f32_e32 v112, 0xbfb8aa3b, v112
	v_mul_f32_e32 v126, v126, v180
	v_mul_f32_e32 v127, v127, v180
	v_add_f32_e32 v175, 1.0, v125
	v_exp_f32_e32 v125, v112
	v_mul_f32_e32 v112, v114, v180
	v_med3_f32 v126, v126, s55, v166
	v_med3_f32 v127, v127, s55, v166
	v_med3_f32 v112, v112, s55, v166
	v_mul_f32_e32 v126, 0xbfb8aa3b, v126
	v_mul_f32_e32 v127, 0xbfb8aa3b, v127
	v_mul_f32_e32 v120, v120, v180
	v_mul_f32_e32 v121, v121, v180
	v_mul_f32_e32 v112, 0xbfb8aa3b, v112
	v_rsq_f32_e32 v173, v168
	v_exp_f32_e32 v126, v126
	v_exp_f32_e32 v127, v127
	v_med3_f32 v120, v120, s55, v166
	v_med3_f32 v121, v121, s55, v166
	v_exp_f32_e32 v114, v112
	v_mul_f32_e32 v112, v115, v180
	v_mul_f32_e32 v120, 0xbfb8aa3b, v120
	v_mul_f32_e32 v121, 0xbfb8aa3b, v121
	v_mul_f32_e32 v122, v122, v180
	v_mul_f32_e32 v123, v123, v180
	v_med3_f32 v112, v112, s55, v166
	v_exp_f32_e32 v120, v120
	v_exp_f32_e32 v121, v121
	v_med3_f32 v122, v122, s55, v166
	v_med3_f32 v123, v123, s55, v166
	v_mul_f32_e32 v112, 0xbfb8aa3b, v112
	v_mul_f32_e32 v167, 0x45800000, v172
	v_mul_f32_e32 v122, 0xbfb8aa3b, v122
	v_mul_f32_e32 v123, 0xbfb8aa3b, v123
	v_exp_f32_e32 v115, v112
	v_rcp_f32_e32 v112, v174
	v_rcp_f32_e32 v113, v175
	v_cndmask_b32_e32 v168, v172, v167, vcc
	v_mul_f32_e32 v167, 0x45800000, v173
	v_add_f32_e32 v126, 1.0, v126
	v_add_f32_e32 v127, 1.0, v127
	v_exp_f32_e32 v122, v122
	v_exp_f32_e32 v123, v123
	v_mul_f32_e32 v116, v116, v180
	v_mul_f32_e32 v117, v117, v180
	v_cndmask_b32_e64 v167, v173, v167, s[6:7]
	s_lshl_b32 s6, s57, 6
	s_lshl_b32 s7, s57, 4
	v_med3_f32 v116, v116, s55, v166
	v_med3_f32 v117, v117, s55, v166
	v_mul_f32_e32 v118, v118, v180
	v_mul_f32_e32 v119, v119, v180
	v_rcp_f32_e32 v126, v126
	v_rcp_f32_e32 v127, v127
	s_and_b32 s6, s6, 0xffffff80
	s_and_b32 s7, s7, 16
	v_mul_f32_e32 v116, 0xbfb8aa3b, v116
	v_mul_f32_e32 v117, 0xbfb8aa3b, v117
	v_med3_f32 v118, v118, s55, v166
	v_med3_f32 v119, v119, s55, v166
	v_pk_add_f32 v[120:121], v[120:121], 1.0 op_sel_hi:[1,0]
	s_or_b32 s6, s7, s6
	v_exp_f32_e32 v116, v116
	v_exp_f32_e32 v117, v117
	v_mul_f32_e32 v118, 0xbfb8aa3b, v118
	v_mul_f32_e32 v119, 0xbfb8aa3b, v119
	v_pk_mul_f32 v[112:113], v[120:121], v[112:113]
	s_and_b32 s98, s6, 0x380
	s_and_b32 s99, s6, 16
	s_lshl_b32 s99, s99, 2
	s_or_b32 s98, s98, s99
	v_lshrrev_b32_e32 v238, 1, v162
	v_and_b32_e32 v238, 48, v238
	v_and_or_b32 v238, v162, 12, v238
	v_or_b32_e32 v172, s98, v238
	v_exp_f32_e32 v118, v118
	v_exp_f32_e32 v119, v119
	v_rcp_f32_e32 v174, v120
	v_cvt_pk_f16_f32 v120, v112, v113
	v_pk_add_f32 v[112:113], v[122:123], 1.0 op_sel_hi:[1,0]
	v_ashrrev_i32_e32 v173, 31, v172
	v_rcp_f32_e32 v175, v121
	v_rcp_f32_e32 v122, v112
	v_rcp_f32_e32 v123, v113
	v_pk_mul_f32 v[112:113], v[112:113], v[126:127]
	v_mul_f32_e32 v108, v108, v176
	v_mul_f32_e32 v109, v109, v176
	v_mul_f32_e32 v110, v110, v176
	v_mul_f32_e32 v111, v111, v176
	v_cvt_pk_f16_f32 v121, v112, v113
	v_lshl_add_u64 v[126:127], s[14:15], 0, v[156:157]
	v_lshlrev_b64 v[112:113], 1, v[172:173]
	v_med3_f32 v108, v108, s55, v166
	v_med3_f32 v109, v109, s55, v166
	v_med3_f32 v110, v110, s55, v166
	v_med3_f32 v111, v111, s55, v166
	v_lshl_add_u64 v[126:127], v[126:127], 0, v[112:113]
	v_pk_add_f32 v[116:117], v[116:117], 1.0 op_sel_hi:[1,0]
	v_mul_f32_e32 v108, 0xbfb8aa3b, v108
	v_mul_f32_e32 v109, 0xbfb8aa3b, v109
	v_mul_f32_e32 v110, 0xbfb8aa3b, v110
	v_mul_f32_e32 v111, 0xbfb8aa3b, v111
	global_store_dwordx2 v[126:127], v[120:121], off
	v_rcp_f32_e32 v120, v116
	v_rcp_f32_e32 v121, v117
	v_pk_add_f32 v[118:119], v[118:119], 1.0 op_sel_hi:[1,0]
	v_exp_f32_e32 v108, v108
	v_exp_f32_e32 v109, v109
	v_exp_f32_e32 v110, v110
	v_exp_f32_e32 v111, v111
	v_pk_mul_f32 v[116:117], v[116:117], v[174:175]
	v_rcp_f32_e32 v156, v118
	v_rcp_f32_e32 v157, v119
	v_pk_mul_f32 v[118:119], v[118:119], v[122:123]
	v_mul_f32_e32 v104, v104, v176
	v_mul_f32_e32 v105, v105, v176
	v_mul_f32_e32 v106, v106, v176
	v_mul_f32_e32 v107, v107, v176
	v_cvt_pk_f16_f32 v116, v116, v117
	v_cvt_pk_f16_f32 v117, v118, v119
	v_med3_f32 v104, v104, s55, v166
	v_med3_f32 v105, v105, s55, v166
	v_med3_f32 v106, v106, s55, v166
	v_med3_f32 v107, v107, s55, v166
	global_store_dwordx2 v[126:127], v[116:117], off offset:2048
	v_pk_add_f32 v[116:117], v[124:125], 1.0 op_sel_hi:[1,0]
	v_pk_add_f32 v[114:115], v[114:115], 1.0 op_sel_hi:[1,0]
	v_mul_f32_e32 v104, 0xbfb8aa3b, v104
	v_mul_f32_e32 v105, 0xbfb8aa3b, v105
	v_mul_f32_e32 v106, 0xbfb8aa3b, v106
	v_mul_f32_e32 v107, 0xbfb8aa3b, v107
	v_rcp_f32_e32 v118, v116
	v_rcp_f32_e32 v119, v117
	v_pk_mul_f32 v[116:117], v[116:117], v[120:121]
	v_rcp_f32_e32 v120, v114
	v_rcp_f32_e32 v121, v115
	v_add_f32_e32 v108, 1.0, v108
	v_add_f32_e32 v109, 1.0, v109
	v_add_f32_e32 v110, 1.0, v110
	v_add_f32_e32 v111, 1.0, v111
	v_exp_f32_e32 v104, v104
	v_exp_f32_e32 v105, v105
	v_exp_f32_e32 v106, v106
	v_exp_f32_e32 v107, v107
	v_mul_f32_e32 v100, v100, v176
	v_mul_f32_e32 v101, v101, v176
	v_mul_f32_e32 v102, v102, v176
	v_mul_f32_e32 v103, v103, v176
	v_pk_mul_f32 v[114:115], v[114:115], v[156:157]
	v_med3_f32 v100, v100, s55, v166
	v_med3_f32 v101, v101, s55, v166
	v_med3_f32 v102, v102, s55, v166
	v_med3_f32 v103, v103, s55, v166
	v_rcp_f32_e32 v108, v108
	v_rcp_f32_e32 v109, v109
	v_rcp_f32_e32 v110, v110
	v_rcp_f32_e32 v111, v111
	v_cvt_pk_f16_f32 v116, v116, v117
	v_cvt_pk_f16_f32 v117, v114, v115
	v_add_co_u32_e32 v114, vcc, s56, v126
	v_mul_f32_e32 v100, 0xbfb8aa3b, v100
	v_mul_f32_e32 v101, 0xbfb8aa3b, v101
	v_mul_f32_e32 v102, 0xbfb8aa3b, v102
	v_mul_f32_e32 v103, 0xbfb8aa3b, v103
	v_addc_co_u32_e32 v115, vcc, 0, v127, vcc
	v_exp_f32_e32 v100, v100
	v_exp_f32_e32 v101, v101
	v_exp_f32_e32 v102, v102
	v_exp_f32_e32 v103, v103
	v_mul_f32_e32 v96, v96, v176
	v_mul_f32_e32 v97, v97, v176
	v_mul_f32_e32 v98, v98, v176
	v_mul_f32_e32 v99, v99, v176
	global_store_dwordx2 v[114:115], v[116:117], off
	v_cvt_pk_f16_f32 v117, v120, v121
	v_cvt_pk_f16_f32 v116, v118, v119
	v_med3_f32 v96, v96, s55, v166
	v_med3_f32 v97, v97, s55, v166
	v_med3_f32 v98, v98, s55, v166
	v_med3_f32 v99, v99, s55, v166
	v_pk_add_f32 v[104:105], v[104:105], 1.0 op_sel_hi:[1,0]
	v_pk_add_f32 v[106:107], v[106:107], 1.0 op_sel_hi:[1,0]
	v_mul_f32_e32 v92, v92, v177
	v_mul_f32_e32 v93, v93, v177
	v_mul_f32_e32 v94, v94, v177
	v_mul_f32_e32 v95, v95, v177
	global_store_dwordx2 v[114:115], v[116:117], off offset:2048
	v_mul_f32_e32 v96, 0xbfb8aa3b, v96
	v_mul_f32_e32 v97, 0xbfb8aa3b, v97
	v_mul_f32_e32 v98, 0xbfb8aa3b, v98
	v_mul_f32_e32 v99, 0xbfb8aa3b, v99
	v_lshlrev_b64 v[114:115], 13, v[154:155]
	v_rcp_f32_e32 v116, v104
	v_rcp_f32_e32 v117, v105
	v_pk_mul_f32 v[104:105], v[104:105], v[108:109]
	v_rcp_f32_e32 v108, v106
	v_rcp_f32_e32 v109, v107
	v_pk_mul_f32 v[106:107], v[106:107], v[110:111]
	v_med3_f32 v92, v92, s55, v166
	v_med3_f32 v93, v93, s55, v166
	v_med3_f32 v94, v94, s55, v166
	v_med3_f32 v95, v95, s55, v166
	v_exp_f32_e32 v96, v96
	v_exp_f32_e32 v97, v97
	v_exp_f32_e32 v98, v98
	v_exp_f32_e32 v99, v99
	v_cvt_pk_f16_f32 v104, v104, v105
	v_cvt_pk_f16_f32 v105, v106, v107
	v_lshl_add_u64 v[106:107], s[14:15], 0, v[114:115]
	v_mul_f32_e32 v92, 0xbfb8aa3b, v92
	v_mul_f32_e32 v93, 0xbfb8aa3b, v93
	v_mul_f32_e32 v94, 0xbfb8aa3b, v94
	v_mul_f32_e32 v95, 0xbfb8aa3b, v95
	v_lshl_add_u64 v[106:107], v[106:107], 0, v[112:113]
	v_pk_add_f32 v[100:101], v[100:101], 1.0 op_sel_hi:[1,0]
	v_pk_add_f32 v[102:103], v[102:103], 1.0 op_sel_hi:[1,0]
	v_exp_f32_e32 v92, v92
	v_exp_f32_e32 v93, v93
	v_exp_f32_e32 v94, v94
	v_exp_f32_e32 v95, v95
	global_store_dwordx2 v[106:107], v[104:105], off
	v_rcp_f32_e32 v104, v100
	v_rcp_f32_e32 v105, v101
	v_rcp_f32_e32 v110, v102
	v_rcp_f32_e32 v111, v103
	v_mul_f32_e32 v88, v88, v177
	v_mul_f32_e32 v89, v89, v177
	v_mul_f32_e32 v90, v90, v177
	v_mul_f32_e32 v91, v91, v177
	v_pk_mul_f32 v[100:101], v[100:101], v[116:117]
	v_pk_mul_f32 v[102:103], v[102:103], v[108:109]
	v_med3_f32 v88, v88, s55, v166
	v_med3_f32 v89, v89, s55, v166
	v_med3_f32 v90, v90, s55, v166
	v_med3_f32 v91, v91, s55, v166
	v_cvt_pk_f16_f32 v100, v100, v101
	v_cvt_pk_f16_f32 v101, v102, v103
	v_pk_add_f32 v[96:97], v[96:97], 1.0 op_sel_hi:[1,0]
	v_pk_add_f32 v[98:99], v[98:99], 1.0 op_sel_hi:[1,0]
	v_mul_f32_e32 v88, 0xbfb8aa3b, v88
	v_mul_f32_e32 v89, 0xbfb8aa3b, v89
	v_mul_f32_e32 v90, 0xbfb8aa3b, v90
	v_mul_f32_e32 v91, 0xbfb8aa3b, v91
	global_store_dwordx2 v[106:107], v[100:101], off offset:2048
	v_rcp_f32_e32 v100, v96
	v_rcp_f32_e32 v101, v97
	v_rcp_f32_e32 v102, v98
	v_rcp_f32_e32 v103, v99
	v_add_f32_e32 v92, 1.0, v92
	v_add_f32_e32 v93, 1.0, v93
	v_add_f32_e32 v94, 1.0, v94
	v_add_f32_e32 v95, 1.0, v95
	v_exp_f32_e32 v88, v88
	v_exp_f32_e32 v89, v89
	v_exp_f32_e32 v90, v90
	v_exp_f32_e32 v91, v91
	v_mul_f32_e32 v84, v84, v177
	v_mul_f32_e32 v85, v85, v177
	v_mul_f32_e32 v86, v86, v177
	v_mul_f32_e32 v87, v87, v177
	v_pk_mul_f32 v[96:97], v[96:97], v[104:105]
	v_pk_mul_f32 v[98:99], v[98:99], v[110:111]
	v_med3_f32 v84, v84, s55, v166
	v_med3_f32 v85, v85, s55, v166
	v_med3_f32 v86, v86, s55, v166
	v_med3_f32 v87, v87, s55, v166
	v_rcp_f32_e32 v92, v92
	v_rcp_f32_e32 v93, v93
	v_rcp_f32_e32 v94, v94
	v_rcp_f32_e32 v95, v95
	v_cvt_pk_f16_f32 v96, v96, v97
	v_cvt_pk_f16_f32 v97, v98, v99
	v_add_co_u32_e32 v98, vcc, s56, v106
	v_mul_f32_e32 v84, 0xbfb8aa3b, v84
	v_mul_f32_e32 v85, 0xbfb8aa3b, v85
	v_mul_f32_e32 v86, 0xbfb8aa3b, v86
	v_mul_f32_e32 v87, 0xbfb8aa3b, v87
	v_addc_co_u32_e32 v99, vcc, 0, v107, vcc
	v_exp_f32_e32 v84, v84
	v_exp_f32_e32 v85, v85
	v_exp_f32_e32 v86, v86
	v_exp_f32_e32 v87, v87
	v_mul_f32_e32 v80, v80, v177
	v_mul_f32_e32 v81, v81, v177
	v_mul_f32_e32 v82, v82, v177
	v_mul_f32_e32 v83, v83, v177
	global_store_dwordx2 v[98:99], v[96:97], off
	v_cvt_pk_f16_f32 v97, v102, v103
	v_cvt_pk_f16_f32 v96, v100, v101
	v_med3_f32 v80, v80, s55, v166
	v_med3_f32 v81, v81, s55, v166
	v_med3_f32 v82, v82, s55, v166
	v_med3_f32 v83, v83, s55, v166
	v_pk_add_f32 v[88:89], v[88:89], 1.0 op_sel_hi:[1,0]
	v_pk_add_f32 v[90:91], v[90:91], 1.0 op_sel_hi:[1,0]
	v_mul_f32_e32 v76, v76, v171
	v_mul_f32_e32 v77, v77, v171
	v_mul_f32_e32 v78, v78, v171
	v_mul_f32_e32 v79, v79, v171
	global_store_dwordx2 v[98:99], v[96:97], off offset:2048
	v_mul_f32_e32 v80, 0xbfb8aa3b, v80
	v_mul_f32_e32 v81, 0xbfb8aa3b, v81
	v_mul_f32_e32 v82, 0xbfb8aa3b, v82
	v_mul_f32_e32 v83, 0xbfb8aa3b, v83
	v_lshlrev_b64 v[96:97], 13, v[152:153]
	v_rcp_f32_e32 v98, v88
	v_rcp_f32_e32 v99, v89
	v_pk_mul_f32 v[88:89], v[88:89], v[92:93]
	v_rcp_f32_e32 v92, v90
	v_rcp_f32_e32 v93, v91
	v_pk_mul_f32 v[90:91], v[90:91], v[94:95]
	v_med3_f32 v76, v76, s55, v166
	v_med3_f32 v77, v77, s55, v166
	v_med3_f32 v78, v78, s55, v166
	v_med3_f32 v79, v79, s55, v166
	v_exp_f32_e32 v80, v80
	v_exp_f32_e32 v81, v81
	v_exp_f32_e32 v82, v82
	v_exp_f32_e32 v83, v83
	v_cvt_pk_f16_f32 v88, v88, v89
	v_cvt_pk_f16_f32 v89, v90, v91
	v_lshl_add_u64 v[90:91], s[14:15], 0, v[96:97]
	v_mul_f32_e32 v76, 0xbfb8aa3b, v76
	v_mul_f32_e32 v77, 0xbfb8aa3b, v77
	v_mul_f32_e32 v78, 0xbfb8aa3b, v78
	v_mul_f32_e32 v79, 0xbfb8aa3b, v79
	v_lshl_add_u64 v[90:91], v[90:91], 0, v[112:113]
	v_pk_add_f32 v[84:85], v[84:85], 1.0 op_sel_hi:[1,0]
	v_pk_add_f32 v[86:87], v[86:87], 1.0 op_sel_hi:[1,0]
	v_exp_f32_e32 v76, v76
	v_exp_f32_e32 v77, v77
	v_exp_f32_e32 v78, v78
	v_exp_f32_e32 v79, v79
	global_store_dwordx2 v[90:91], v[88:89], off
	v_rcp_f32_e32 v88, v84
	v_rcp_f32_e32 v89, v85
	v_rcp_f32_e32 v94, v86
	v_rcp_f32_e32 v95, v87
	v_mul_f32_e32 v72, v72, v171
	v_mul_f32_e32 v73, v73, v171
	v_mul_f32_e32 v74, v74, v171
	v_mul_f32_e32 v75, v75, v171
	v_pk_mul_f32 v[84:85], v[84:85], v[98:99]
	v_pk_mul_f32 v[86:87], v[86:87], v[92:93]
	v_med3_f32 v72, v72, s55, v166
	v_med3_f32 v73, v73, s55, v166
	v_med3_f32 v74, v74, s55, v166
	v_med3_f32 v75, v75, s55, v166
	v_cvt_pk_f16_f32 v84, v84, v85
	v_cvt_pk_f16_f32 v85, v86, v87
	v_pk_add_f32 v[80:81], v[80:81], 1.0 op_sel_hi:[1,0]
	v_pk_add_f32 v[82:83], v[82:83], 1.0 op_sel_hi:[1,0]
	v_mul_f32_e32 v72, 0xbfb8aa3b, v72
	v_mul_f32_e32 v73, 0xbfb8aa3b, v73
	v_mul_f32_e32 v74, 0xbfb8aa3b, v74
	v_mul_f32_e32 v75, 0xbfb8aa3b, v75
	global_store_dwordx2 v[90:91], v[84:85], off offset:2048
	v_rcp_f32_e32 v84, v80
	v_rcp_f32_e32 v85, v81
	v_rcp_f32_e32 v86, v82
	v_rcp_f32_e32 v87, v83
	v_add_f32_e32 v76, 1.0, v76
	v_add_f32_e32 v77, 1.0, v77
	v_add_f32_e32 v78, 1.0, v78
	v_add_f32_e32 v79, 1.0, v79
	v_exp_f32_e32 v72, v72
	v_exp_f32_e32 v73, v73
	v_exp_f32_e32 v74, v74
	v_exp_f32_e32 v75, v75
	v_mul_f32_e32 v68, v68, v171
	v_mul_f32_e32 v69, v69, v171
	v_mul_f32_e32 v70, v70, v171
	v_mul_f32_e32 v71, v71, v171
	v_pk_mul_f32 v[80:81], v[80:81], v[88:89]
	v_pk_mul_f32 v[82:83], v[82:83], v[94:95]
	v_med3_f32 v68, v68, s55, v166
	v_med3_f32 v69, v69, s55, v166
	v_med3_f32 v70, v70, s55, v166
	v_med3_f32 v71, v71, s55, v166
	v_rcp_f32_e32 v76, v76
	v_rcp_f32_e32 v77, v77
	v_rcp_f32_e32 v78, v78
	v_rcp_f32_e32 v79, v79
	v_cvt_pk_f16_f32 v80, v80, v81
	v_cvt_pk_f16_f32 v81, v82, v83
	v_add_co_u32_e32 v82, vcc, s56, v90
	v_mul_f32_e32 v68, 0xbfb8aa3b, v68
	v_mul_f32_e32 v69, 0xbfb8aa3b, v69
	v_mul_f32_e32 v70, 0xbfb8aa3b, v70
	v_mul_f32_e32 v71, 0xbfb8aa3b, v71
	v_addc_co_u32_e32 v83, vcc, 0, v91, vcc
	v_exp_f32_e32 v68, v68
	v_exp_f32_e32 v69, v69
	v_exp_f32_e32 v70, v70
	v_exp_f32_e32 v71, v71
	v_mul_f32_e32 v64, v64, v171
	v_mul_f32_e32 v65, v65, v171
	v_mul_f32_e32 v66, v66, v171
	v_mul_f32_e32 v67, v67, v171
	global_store_dwordx2 v[82:83], v[80:81], off
	v_cvt_pk_f16_f32 v81, v86, v87
	v_cvt_pk_f16_f32 v80, v84, v85
	v_med3_f32 v64, v64, s55, v166
	v_med3_f32 v65, v65, s55, v166
	v_med3_f32 v66, v66, s55, v166
	v_med3_f32 v67, v67, s55, v166
	v_pk_add_f32 v[72:73], v[72:73], 1.0 op_sel_hi:[1,0]
	v_pk_add_f32 v[74:75], v[74:75], 1.0 op_sel_hi:[1,0]
	v_mul_f32_e32 v60, v60, v170
	v_mul_f32_e32 v61, v61, v170
	v_mul_f32_e32 v62, v62, v170
	v_mul_f32_e32 v63, v63, v170
	global_store_dwordx2 v[82:83], v[80:81], off offset:2048
	v_mul_f32_e32 v64, 0xbfb8aa3b, v64
	v_mul_f32_e32 v65, 0xbfb8aa3b, v65
	v_mul_f32_e32 v66, 0xbfb8aa3b, v66
	v_mul_f32_e32 v67, 0xbfb8aa3b, v67
	v_lshlrev_b64 v[80:81], 13, v[150:151]
	v_rcp_f32_e32 v82, v72
	v_rcp_f32_e32 v83, v73
	v_pk_mul_f32 v[72:73], v[72:73], v[76:77]
	v_rcp_f32_e32 v76, v74
	v_rcp_f32_e32 v77, v75
	v_pk_mul_f32 v[74:75], v[74:75], v[78:79]
	v_med3_f32 v60, v60, s55, v166
	v_med3_f32 v61, v61, s55, v166
	v_med3_f32 v62, v62, s55, v166
	v_med3_f32 v63, v63, s55, v166
	v_exp_f32_e32 v64, v64
	v_exp_f32_e32 v65, v65
	v_exp_f32_e32 v66, v66
	v_exp_f32_e32 v67, v67
	v_cvt_pk_f16_f32 v72, v72, v73
	v_cvt_pk_f16_f32 v73, v74, v75
	v_lshl_add_u64 v[74:75], s[14:15], 0, v[80:81]
	v_mul_f32_e32 v60, 0xbfb8aa3b, v60
	v_mul_f32_e32 v61, 0xbfb8aa3b, v61
	v_mul_f32_e32 v62, 0xbfb8aa3b, v62
	v_mul_f32_e32 v63, 0xbfb8aa3b, v63
	v_lshl_add_u64 v[74:75], v[74:75], 0, v[112:113]
	v_pk_add_f32 v[68:69], v[68:69], 1.0 op_sel_hi:[1,0]
	v_pk_add_f32 v[70:71], v[70:71], 1.0 op_sel_hi:[1,0]
	v_exp_f32_e32 v60, v60
	v_exp_f32_e32 v61, v61
	v_exp_f32_e32 v62, v62
	v_exp_f32_e32 v63, v63
	global_store_dwordx2 v[74:75], v[72:73], off
	v_rcp_f32_e32 v72, v68
	v_rcp_f32_e32 v73, v69
	v_rcp_f32_e32 v78, v70
	v_rcp_f32_e32 v79, v71
	v_mul_f32_e32 v56, v56, v170
	v_mul_f32_e32 v57, v57, v170
	v_mul_f32_e32 v58, v58, v170
	v_mul_f32_e32 v59, v59, v170
	v_pk_mul_f32 v[68:69], v[68:69], v[82:83]
	v_pk_mul_f32 v[70:71], v[70:71], v[76:77]
	v_med3_f32 v56, v56, s55, v166
	v_med3_f32 v57, v57, s55, v166
	v_med3_f32 v58, v58, s55, v166
	v_med3_f32 v59, v59, s55, v166
	v_cvt_pk_f16_f32 v68, v68, v69
	v_cvt_pk_f16_f32 v69, v70, v71
	v_pk_add_f32 v[64:65], v[64:65], 1.0 op_sel_hi:[1,0]
	v_pk_add_f32 v[66:67], v[66:67], 1.0 op_sel_hi:[1,0]
	v_mul_f32_e32 v56, 0xbfb8aa3b, v56
	v_mul_f32_e32 v57, 0xbfb8aa3b, v57
	v_mul_f32_e32 v58, 0xbfb8aa3b, v58
	v_mul_f32_e32 v59, 0xbfb8aa3b, v59
	global_store_dwordx2 v[74:75], v[68:69], off offset:2048
	v_rcp_f32_e32 v68, v64
	v_rcp_f32_e32 v69, v65
	v_rcp_f32_e32 v70, v66
	v_rcp_f32_e32 v71, v67
	v_add_f32_e32 v60, 1.0, v60
	v_add_f32_e32 v61, 1.0, v61
	v_add_f32_e32 v62, 1.0, v62
	v_add_f32_e32 v63, 1.0, v63
	v_exp_f32_e32 v56, v56
	v_exp_f32_e32 v57, v57
	v_exp_f32_e32 v58, v58
	v_exp_f32_e32 v59, v59
	v_mul_f32_e32 v52, v52, v170
	v_mul_f32_e32 v53, v53, v170
	v_mul_f32_e32 v54, v54, v170
	v_mul_f32_e32 v55, v55, v170
	v_pk_mul_f32 v[64:65], v[64:65], v[72:73]
	v_pk_mul_f32 v[66:67], v[66:67], v[78:79]
	v_med3_f32 v52, v52, s55, v166
	v_med3_f32 v53, v53, s55, v166
	v_med3_f32 v54, v54, s55, v166
	v_med3_f32 v55, v55, s55, v166
	v_rcp_f32_e32 v60, v60
	v_rcp_f32_e32 v61, v61
	v_rcp_f32_e32 v62, v62
	v_rcp_f32_e32 v63, v63
	v_cvt_pk_f16_f32 v64, v64, v65
	v_cvt_pk_f16_f32 v65, v66, v67
	v_add_co_u32_e32 v66, vcc, s56, v74
	v_mul_f32_e32 v52, 0xbfb8aa3b, v52
	v_mul_f32_e32 v53, 0xbfb8aa3b, v53
	v_mul_f32_e32 v54, 0xbfb8aa3b, v54
	v_mul_f32_e32 v55, 0xbfb8aa3b, v55
	v_addc_co_u32_e32 v67, vcc, 0, v75, vcc
	v_exp_f32_e32 v52, v52
	v_exp_f32_e32 v53, v53
	v_exp_f32_e32 v54, v54
	v_exp_f32_e32 v55, v55
	v_mul_f32_e32 v48, v48, v170
	v_mul_f32_e32 v49, v49, v170
	v_mul_f32_e32 v50, v50, v170
	v_mul_f32_e32 v51, v51, v170
	global_store_dwordx2 v[66:67], v[64:65], off
	v_cvt_pk_f16_f32 v65, v70, v71
	v_cvt_pk_f16_f32 v64, v68, v69
	v_med3_f32 v48, v48, s55, v166
	v_med3_f32 v49, v49, s55, v166
	v_med3_f32 v50, v50, s55, v166
	v_med3_f32 v51, v51, s55, v166
	v_pk_add_f32 v[56:57], v[56:57], 1.0 op_sel_hi:[1,0]
	v_pk_add_f32 v[58:59], v[58:59], 1.0 op_sel_hi:[1,0]
	v_mul_f32_e32 v44, v44, v169
	v_mul_f32_e32 v45, v45, v169
	v_mul_f32_e32 v46, v46, v169
	v_mul_f32_e32 v47, v47, v169
	global_store_dwordx2 v[66:67], v[64:65], off offset:2048
	v_mul_f32_e32 v48, 0xbfb8aa3b, v48
	v_mul_f32_e32 v49, 0xbfb8aa3b, v49
	v_mul_f32_e32 v50, 0xbfb8aa3b, v50
	v_mul_f32_e32 v51, 0xbfb8aa3b, v51
	v_lshlrev_b64 v[64:65], 13, v[148:149]
	v_rcp_f32_e32 v66, v56
	v_rcp_f32_e32 v67, v57
	v_pk_mul_f32 v[56:57], v[56:57], v[60:61]
	v_rcp_f32_e32 v60, v58
	v_rcp_f32_e32 v61, v59
	v_pk_mul_f32 v[58:59], v[58:59], v[62:63]
	v_med3_f32 v44, v44, s55, v166
	v_med3_f32 v45, v45, s55, v166
	v_med3_f32 v46, v46, s55, v166
	v_med3_f32 v47, v47, s55, v166
	v_exp_f32_e32 v48, v48
	v_exp_f32_e32 v49, v49
	v_exp_f32_e32 v50, v50
	v_exp_f32_e32 v51, v51
	v_cvt_pk_f16_f32 v56, v56, v57
	v_cvt_pk_f16_f32 v57, v58, v59
	v_lshl_add_u64 v[58:59], s[14:15], 0, v[64:65]
	v_mul_f32_e32 v44, 0xbfb8aa3b, v44
	v_mul_f32_e32 v45, 0xbfb8aa3b, v45
	v_mul_f32_e32 v46, 0xbfb8aa3b, v46
	v_mul_f32_e32 v47, 0xbfb8aa3b, v47
	v_lshl_add_u64 v[58:59], v[58:59], 0, v[112:113]
	v_pk_add_f32 v[52:53], v[52:53], 1.0 op_sel_hi:[1,0]
	v_pk_add_f32 v[54:55], v[54:55], 1.0 op_sel_hi:[1,0]
	v_exp_f32_e32 v44, v44
	v_exp_f32_e32 v45, v45
	v_exp_f32_e32 v46, v46
	v_exp_f32_e32 v47, v47
	global_store_dwordx2 v[58:59], v[56:57], off
	v_rcp_f32_e32 v56, v52
	v_rcp_f32_e32 v57, v53
	v_rcp_f32_e32 v62, v54
	v_rcp_f32_e32 v63, v55
	v_mul_f32_e32 v40, v40, v169
	v_mul_f32_e32 v41, v41, v169
	v_mul_f32_e32 v42, v42, v169
	v_mul_f32_e32 v43, v43, v169
	v_pk_mul_f32 v[52:53], v[52:53], v[66:67]
	v_pk_mul_f32 v[54:55], v[54:55], v[60:61]
	v_med3_f32 v40, v40, s55, v166
	v_med3_f32 v41, v41, s55, v166
	v_med3_f32 v42, v42, s55, v166
	v_med3_f32 v43, v43, s55, v166
	v_cvt_pk_f16_f32 v52, v52, v53
	v_cvt_pk_f16_f32 v53, v54, v55
	v_pk_add_f32 v[48:49], v[48:49], 1.0 op_sel_hi:[1,0]
	v_pk_add_f32 v[50:51], v[50:51], 1.0 op_sel_hi:[1,0]
	v_mul_f32_e32 v40, 0xbfb8aa3b, v40
	v_mul_f32_e32 v41, 0xbfb8aa3b, v41
	v_mul_f32_e32 v42, 0xbfb8aa3b, v42
	v_mul_f32_e32 v43, 0xbfb8aa3b, v43
	global_store_dwordx2 v[58:59], v[52:53], off offset:2048
	v_rcp_f32_e32 v52, v48
	v_rcp_f32_e32 v53, v49
	v_rcp_f32_e32 v54, v50
	v_rcp_f32_e32 v55, v51
	v_add_f32_e32 v44, 1.0, v44
	v_add_f32_e32 v45, 1.0, v45
	v_add_f32_e32 v46, 1.0, v46
	v_add_f32_e32 v47, 1.0, v47
	v_exp_f32_e32 v40, v40
	v_exp_f32_e32 v41, v41
	v_exp_f32_e32 v42, v42
	v_exp_f32_e32 v43, v43
	v_mul_f32_e32 v36, v36, v169
	v_mul_f32_e32 v37, v37, v169
	v_mul_f32_e32 v38, v38, v169
	v_mul_f32_e32 v39, v39, v169
	v_pk_mul_f32 v[48:49], v[48:49], v[56:57]
	v_pk_mul_f32 v[50:51], v[50:51], v[62:63]
	v_med3_f32 v36, v36, s55, v166
	v_med3_f32 v37, v37, s55, v166
	v_med3_f32 v38, v38, s55, v166
	v_med3_f32 v39, v39, s55, v166
	v_rcp_f32_e32 v44, v44
	v_rcp_f32_e32 v45, v45
	v_rcp_f32_e32 v46, v46
	v_rcp_f32_e32 v47, v47
	v_cvt_pk_f16_f32 v48, v48, v49
	v_cvt_pk_f16_f32 v49, v50, v51
	v_add_co_u32_e32 v50, vcc, s56, v58
	v_mul_f32_e32 v36, 0xbfb8aa3b, v36
	v_mul_f32_e32 v37, 0xbfb8aa3b, v37
	v_mul_f32_e32 v38, 0xbfb8aa3b, v38
	v_mul_f32_e32 v39, 0xbfb8aa3b, v39
	v_addc_co_u32_e32 v51, vcc, 0, v59, vcc
	v_exp_f32_e32 v36, v36
	v_exp_f32_e32 v37, v37
	v_exp_f32_e32 v38, v38
	v_exp_f32_e32 v39, v39
	v_mul_f32_e32 v32, v32, v169
	v_mul_f32_e32 v33, v33, v169
	v_mul_f32_e32 v34, v34, v169
	v_mul_f32_e32 v35, v35, v169
	global_store_dwordx2 v[50:51], v[48:49], off
	v_cvt_pk_f16_f32 v49, v54, v55
	v_cvt_pk_f16_f32 v48, v52, v53
	v_med3_f32 v32, v32, s55, v166
	v_med3_f32 v33, v33, s55, v166
	v_med3_f32 v34, v34, s55, v166
	v_med3_f32 v35, v35, s55, v166
	v_pk_add_f32 v[40:41], v[40:41], 1.0 op_sel_hi:[1,0]
	v_pk_add_f32 v[42:43], v[42:43], 1.0 op_sel_hi:[1,0]
	v_mul_f32_e32 v28, v28, v168
	v_mul_f32_e32 v29, v29, v168
	v_mul_f32_e32 v30, v30, v168
	v_mul_f32_e32 v31, v31, v168
	global_store_dwordx2 v[50:51], v[48:49], off offset:2048
	v_mul_f32_e32 v32, 0xbfb8aa3b, v32
	v_mul_f32_e32 v33, 0xbfb8aa3b, v33
	v_mul_f32_e32 v34, 0xbfb8aa3b, v34
	v_mul_f32_e32 v35, 0xbfb8aa3b, v35
	v_lshlrev_b64 v[48:49], 13, v[146:147]
	v_rcp_f32_e32 v50, v40
	v_rcp_f32_e32 v51, v41
	v_pk_mul_f32 v[40:41], v[40:41], v[44:45]
	v_rcp_f32_e32 v44, v42
	v_rcp_f32_e32 v45, v43
	v_pk_mul_f32 v[42:43], v[42:43], v[46:47]
	v_med3_f32 v28, v28, s55, v166
	v_med3_f32 v29, v29, s55, v166
	v_med3_f32 v30, v30, s55, v166
	v_med3_f32 v31, v31, s55, v166
	v_exp_f32_e32 v32, v32
	v_exp_f32_e32 v33, v33
	v_exp_f32_e32 v34, v34
	v_exp_f32_e32 v35, v35
	v_cvt_pk_f16_f32 v40, v40, v41
	v_cvt_pk_f16_f32 v41, v42, v43
	v_lshl_add_u64 v[42:43], s[14:15], 0, v[48:49]
	v_mul_f32_e32 v28, 0xbfb8aa3b, v28
	v_mul_f32_e32 v29, 0xbfb8aa3b, v29
	v_mul_f32_e32 v30, 0xbfb8aa3b, v30
	v_mul_f32_e32 v31, 0xbfb8aa3b, v31
	v_lshl_add_u64 v[42:43], v[42:43], 0, v[112:113]
	v_pk_add_f32 v[36:37], v[36:37], 1.0 op_sel_hi:[1,0]
	v_pk_add_f32 v[38:39], v[38:39], 1.0 op_sel_hi:[1,0]
	v_exp_f32_e32 v28, v28
	v_exp_f32_e32 v29, v29
	v_exp_f32_e32 v30, v30
	v_exp_f32_e32 v31, v31
	global_store_dwordx2 v[42:43], v[40:41], off
	v_rcp_f32_e32 v40, v36
	v_rcp_f32_e32 v41, v37
	v_rcp_f32_e32 v46, v38
	v_rcp_f32_e32 v47, v39
	v_mul_f32_e32 v24, v24, v168
	v_mul_f32_e32 v25, v25, v168
	v_mul_f32_e32 v26, v26, v168
	v_mul_f32_e32 v27, v27, v168
	v_pk_mul_f32 v[36:37], v[36:37], v[50:51]
	v_pk_mul_f32 v[38:39], v[38:39], v[44:45]
	v_med3_f32 v24, v24, s55, v166
	v_med3_f32 v25, v25, s55, v166
	v_med3_f32 v26, v26, s55, v166
	v_med3_f32 v27, v27, s55, v166
	v_cvt_pk_f16_f32 v36, v36, v37
	v_cvt_pk_f16_f32 v37, v38, v39
	v_pk_add_f32 v[32:33], v[32:33], 1.0 op_sel_hi:[1,0]
	v_pk_add_f32 v[34:35], v[34:35], 1.0 op_sel_hi:[1,0]
	v_mul_f32_e32 v24, 0xbfb8aa3b, v24
	v_mul_f32_e32 v25, 0xbfb8aa3b, v25
	v_mul_f32_e32 v26, 0xbfb8aa3b, v26
	v_mul_f32_e32 v27, 0xbfb8aa3b, v27
	global_store_dwordx2 v[42:43], v[36:37], off offset:2048
	v_rcp_f32_e32 v36, v32
	v_rcp_f32_e32 v37, v33
	v_rcp_f32_e32 v38, v34
	v_rcp_f32_e32 v39, v35
	v_add_f32_e32 v28, 1.0, v28
	v_add_f32_e32 v29, 1.0, v29
	v_add_f32_e32 v30, 1.0, v30
	v_add_f32_e32 v31, 1.0, v31
	v_exp_f32_e32 v24, v24
	v_exp_f32_e32 v25, v25
	v_exp_f32_e32 v26, v26
	v_exp_f32_e32 v27, v27
	v_mul_f32_e32 v20, v20, v168
	v_mul_f32_e32 v21, v21, v168
	v_mul_f32_e32 v22, v22, v168
	v_mul_f32_e32 v23, v23, v168
	v_pk_mul_f32 v[32:33], v[32:33], v[40:41]
	v_pk_mul_f32 v[34:35], v[34:35], v[46:47]
	v_med3_f32 v20, v20, s55, v166
	v_med3_f32 v21, v21, s55, v166
	v_med3_f32 v22, v22, s55, v166
	v_med3_f32 v23, v23, s55, v166
	v_rcp_f32_e32 v28, v28
	v_rcp_f32_e32 v29, v29
	v_rcp_f32_e32 v30, v30
	v_rcp_f32_e32 v31, v31
	v_cvt_pk_f16_f32 v32, v32, v33
	v_cvt_pk_f16_f32 v33, v34, v35
	v_add_co_u32_e32 v34, vcc, s56, v42
	v_mul_f32_e32 v20, 0xbfb8aa3b, v20
	v_mul_f32_e32 v21, 0xbfb8aa3b, v21
	v_mul_f32_e32 v22, 0xbfb8aa3b, v22
	v_mul_f32_e32 v23, 0xbfb8aa3b, v23
	v_addc_co_u32_e32 v35, vcc, 0, v43, vcc
	v_exp_f32_e32 v20, v20
	v_exp_f32_e32 v21, v21
	v_exp_f32_e32 v22, v22
	v_exp_f32_e32 v23, v23
	v_mul_f32_e32 v16, v16, v168
	v_mul_f32_e32 v17, v17, v168
	v_mul_f32_e32 v18, v18, v168
	v_mul_f32_e32 v19, v19, v168
	global_store_dwordx2 v[34:35], v[32:33], off
	v_cvt_pk_f16_f32 v33, v38, v39
	v_cvt_pk_f16_f32 v32, v36, v37
	v_med3_f32 v16, v16, s55, v166
	v_med3_f32 v17, v17, s55, v166
	v_med3_f32 v18, v18, s55, v166
	v_med3_f32 v19, v19, s55, v166
	v_pk_add_f32 v[24:25], v[24:25], 1.0 op_sel_hi:[1,0]
	v_pk_add_f32 v[26:27], v[26:27], 1.0 op_sel_hi:[1,0]
	v_mul_f32_e32 v12, v12, v167
	v_mul_f32_e32 v13, v13, v167
	v_mul_f32_e32 v14, v14, v167
	v_mul_f32_e32 v15, v15, v167
	global_store_dwordx2 v[34:35], v[32:33], off offset:2048
	v_mul_f32_e32 v16, 0xbfb8aa3b, v16
	v_mul_f32_e32 v17, 0xbfb8aa3b, v17
	v_mul_f32_e32 v18, 0xbfb8aa3b, v18
	v_mul_f32_e32 v19, 0xbfb8aa3b, v19
	v_lshlrev_b64 v[32:33], 13, v[144:145]
	v_rcp_f32_e32 v34, v24
	v_rcp_f32_e32 v35, v25
	v_pk_mul_f32 v[24:25], v[24:25], v[28:29]
	v_rcp_f32_e32 v28, v26
	v_rcp_f32_e32 v29, v27
	v_pk_mul_f32 v[26:27], v[26:27], v[30:31]
	v_med3_f32 v12, v12, s55, v166
	v_med3_f32 v13, v13, s55, v166
	v_med3_f32 v14, v14, s55, v166
	v_med3_f32 v15, v15, s55, v166
	v_exp_f32_e32 v16, v16
	v_exp_f32_e32 v17, v17
	v_exp_f32_e32 v18, v18
	v_exp_f32_e32 v19, v19
	v_cvt_pk_f16_f32 v24, v24, v25
	v_cvt_pk_f16_f32 v25, v26, v27
	v_lshl_add_u64 v[26:27], s[14:15], 0, v[32:33]
	v_mul_f32_e32 v12, 0xbfb8aa3b, v12
	v_mul_f32_e32 v13, 0xbfb8aa3b, v13
	v_mul_f32_e32 v14, 0xbfb8aa3b, v14
	v_mul_f32_e32 v15, 0xbfb8aa3b, v15
	v_lshl_add_u64 v[26:27], v[26:27], 0, v[112:113]
	v_pk_add_f32 v[20:21], v[20:21], 1.0 op_sel_hi:[1,0]
	v_pk_add_f32 v[22:23], v[22:23], 1.0 op_sel_hi:[1,0]
	v_exp_f32_e32 v12, v12
	v_exp_f32_e32 v13, v13
	v_exp_f32_e32 v14, v14
	v_exp_f32_e32 v15, v15
	global_store_dwordx2 v[26:27], v[24:25], off
	v_rcp_f32_e32 v24, v20
	v_rcp_f32_e32 v25, v21
	v_rcp_f32_e32 v30, v22
	v_rcp_f32_e32 v31, v23
	v_mul_f32_e32 v8, v8, v167
	v_mul_f32_e32 v9, v9, v167
	v_mul_f32_e32 v10, v10, v167
	v_mul_f32_e32 v11, v11, v167
	v_pk_mul_f32 v[20:21], v[20:21], v[34:35]
	v_pk_mul_f32 v[22:23], v[22:23], v[28:29]
	v_med3_f32 v8, v8, s55, v166
	v_med3_f32 v9, v9, s55, v166
	v_med3_f32 v10, v10, s55, v166
	v_med3_f32 v11, v11, s55, v166
	v_cvt_pk_f16_f32 v20, v20, v21
	v_cvt_pk_f16_f32 v21, v22, v23
	v_pk_add_f32 v[16:17], v[16:17], 1.0 op_sel_hi:[1,0]
	v_pk_add_f32 v[18:19], v[18:19], 1.0 op_sel_hi:[1,0]
	v_mul_f32_e32 v8, 0xbfb8aa3b, v8
	v_mul_f32_e32 v9, 0xbfb8aa3b, v9
	v_mul_f32_e32 v10, 0xbfb8aa3b, v10
	v_mul_f32_e32 v11, 0xbfb8aa3b, v11
	global_store_dwordx2 v[26:27], v[20:21], off offset:2048
	v_rcp_f32_e32 v20, v16
	v_rcp_f32_e32 v21, v17
	v_rcp_f32_e32 v22, v18
	v_rcp_f32_e32 v23, v19
	v_add_f32_e32 v12, 1.0, v12
	v_add_f32_e32 v13, 1.0, v13
	v_add_f32_e32 v14, 1.0, v14
	v_add_f32_e32 v15, 1.0, v15
	v_exp_f32_e32 v8, v8
	v_exp_f32_e32 v9, v9
	v_exp_f32_e32 v10, v10
	v_exp_f32_e32 v11, v11
	v_mul_f32_e32 v4, v4, v167
	v_mul_f32_e32 v5, v5, v167
	v_mul_f32_e32 v6, v6, v167
	v_mul_f32_e32 v7, v7, v167
	v_pk_mul_f32 v[16:17], v[16:17], v[24:25]
	v_pk_mul_f32 v[18:19], v[18:19], v[30:31]
	v_med3_f32 v4, v4, s55, v166
	v_med3_f32 v5, v5, s55, v166
	v_med3_f32 v6, v6, s55, v166
	v_med3_f32 v7, v7, s55, v166
	v_rcp_f32_e32 v12, v12
	v_rcp_f32_e32 v13, v13
	v_rcp_f32_e32 v14, v14
	v_rcp_f32_e32 v15, v15
	v_cvt_pk_f16_f32 v16, v16, v17
	v_cvt_pk_f16_f32 v17, v18, v19
	v_add_co_u32_e32 v18, vcc, s56, v26
	v_mul_f32_e32 v4, 0xbfb8aa3b, v4
	v_mul_f32_e32 v5, 0xbfb8aa3b, v5
	v_mul_f32_e32 v6, 0xbfb8aa3b, v6
	v_mul_f32_e32 v7, 0xbfb8aa3b, v7
	v_addc_co_u32_e32 v19, vcc, 0, v27, vcc
	v_exp_f32_e32 v4, v4
	v_exp_f32_e32 v5, v5
	v_exp_f32_e32 v6, v6
	v_exp_f32_e32 v7, v7
	v_mul_f32_e32 v0, v0, v167
	v_mul_f32_e32 v1, v1, v167
	v_mul_f32_e32 v2, v2, v167
	v_mul_f32_e32 v3, v3, v167
	global_store_dwordx2 v[18:19], v[16:17], off
	v_cvt_pk_f16_f32 v17, v22, v23
	v_cvt_pk_f16_f32 v16, v20, v21
	v_med3_f32 v0, v0, s55, v166
	v_med3_f32 v1, v1, s55, v166
	v_med3_f32 v2, v2, s55, v166
	v_med3_f32 v3, v3, s55, v166
	v_pk_add_f32 v[8:9], v[8:9], 1.0 op_sel_hi:[1,0]
	v_pk_add_f32 v[10:11], v[10:11], 1.0 op_sel_hi:[1,0]
	global_store_dwordx2 v[18:19], v[16:17], off offset:2048
	v_mul_f32_e32 v0, 0xbfb8aa3b, v0
	v_mul_f32_e32 v1, 0xbfb8aa3b, v1
	v_mul_f32_e32 v2, 0xbfb8aa3b, v2
	v_mul_f32_e32 v3, 0xbfb8aa3b, v3
	v_lshlrev_b64 v[16:17], 13, v[142:143]
	v_rcp_f32_e32 v18, v8
	v_rcp_f32_e32 v19, v9
	v_pk_mul_f32 v[8:9], v[8:9], v[12:13]
	v_rcp_f32_e32 v12, v10
	v_rcp_f32_e32 v13, v11
	v_pk_mul_f32 v[10:11], v[10:11], v[14:15]
	v_exp_f32_e32 v0, v0
	v_exp_f32_e32 v1, v1
	v_exp_f32_e32 v2, v2
	v_exp_f32_e32 v3, v3
	v_cvt_pk_f16_f32 v8, v8, v9
	v_cvt_pk_f16_f32 v9, v10, v11
	v_lshl_add_u64 v[10:11], s[14:15], 0, v[16:17]
	v_lshl_add_u64 v[10:11], v[10:11], 0, v[112:113]
	v_pk_add_f32 v[4:5], v[4:5], 1.0 op_sel_hi:[1,0]
	v_pk_add_f32 v[6:7], v[6:7], 1.0 op_sel_hi:[1,0]
	global_store_dwordx2 v[10:11], v[8:9], off
	v_rcp_f32_e32 v8, v4
	v_rcp_f32_e32 v9, v5
	v_rcp_f32_e32 v14, v6
	v_rcp_f32_e32 v15, v7
	v_pk_mul_f32 v[4:5], v[4:5], v[18:19]
	v_pk_mul_f32 v[6:7], v[6:7], v[12:13]
	v_cvt_pk_f16_f32 v4, v4, v5
	v_cvt_pk_f16_f32 v5, v6, v7
	v_pk_add_f32 v[0:1], v[0:1], 1.0 op_sel_hi:[1,0]
	v_pk_add_f32 v[2:3], v[2:3], 1.0 op_sel_hi:[1,0]
	global_store_dwordx2 v[10:11], v[4:5], off offset:2048
	v_rcp_f32_e32 v4, v0
	v_rcp_f32_e32 v5, v1
	v_rcp_f32_e32 v6, v2
	v_rcp_f32_e32 v7, v3
	v_pk_mul_f32 v[0:1], v[0:1], v[8:9]
	v_pk_mul_f32 v[2:3], v[2:3], v[14:15]
	v_cvt_pk_f16_f32 v0, v0, v1
	v_cvt_pk_f16_f32 v1, v2, v3
	v_add_co_u32_e32 v2, vcc, 0x1000, v10
	s_nop 1
	v_addc_co_u32_e32 v3, vcc, 0, v11, vcc
	global_store_dwordx2 v[2:3], v[0:1], off
	v_cvt_pk_f16_f32 v1, v6, v7
	v_cvt_pk_f16_f32 v0, v4, v5
	s_andn2_b64 vcc, exec, s[4:5]
	s_mov_b64 s[4:5], -1
	global_store_dwordx2 v[2:3], v[0:1], off offset:2048
	s_cbranch_vccnz .LBB0_1213
	s_andn2_b64 vcc, exec, s[12:13]
	s_cbranch_vccnz .LBB0_1212
	s_barrier
	s_branch .LBB0_1212

.LBB0_2595:
	s_load_dwordx2 s[98:99], s[88:89], 0x150
	s_waitcnt lgkmcnt(0)
	s_add_u32 s98, s98, 0x400000
	s_addc_u32 s99, s99, 0
	v_mad_u64_u32 v[16:17], s[36:37], v18, s31, v[16:17]
	global_load_dwordx4 v[34:37], v[16:17], off
	v_add_u32_e32 v18, 0x14a0, v33
	s_and_b32 s7, 0xffff, s7
	v_add_u32_e32 v33, 0x14a8, v33
	s_lshl_b32 s10, s6, 1
	s_lshr_b32 s36, s7, 4
	v_lshl_add_u64 v[42:43], v[2:3], 0, s[10:11]
	s_lshr_b32 s6, s7, 6
	s_lshl_b32 s10, s7, 2
	s_and_b32 s7, s7, 0x60
	s_and_b32 s36, s36, 0x80
	s_and_b32 s6, s6, 16
	s_or_b32 s37, s36, s7
	s_and_b32 s10, s10, 0xe00
	s_or_b32 s37, s37, s6
	s_or_b32 s37, s37, s10
	v_mov_b32_e32 v41, v1
	v_mov_b32_e32 v45, v1
	s_waitcnt vmcnt(0)
	v_pk_mul_f32 v[34:35], v[34:35], v[20:21] op_sel_hi:[1,0]
	v_pk_mul_f32 v[16:17], v[36:37], v[20:21] op_sel_hi:[1,0]
	ds_write2_b32 v18, v34, v35 offset1:1
	ds_write2_b32 v33, v16, v17 offset1:1
	s_waitcnt lgkmcnt(0)
	ds_read2_b32 v[16:17], v29 offset1:33
	s_waitcnt lgkmcnt(0)
	v_cvt_pk_bf16_f32 v34, v16, v17
	ds_read2_b32 v[16:17], v29 offset0:66 offset1:99
	s_waitcnt lgkmcnt(0)
	v_cvt_pk_bf16_f32 v35, v16, v17
	ds_read2_b32 v[16:17], v29 offset0:132 offset1:165
	v_or_b32_e32 v18, s37, v9
	s_waitcnt lgkmcnt(0)
	v_cvt_pk_bf16_f32 v36, v16, v17
	ds_read2_b32 v[16:17], v29 offset0:198 offset1:231
	v_lshlrev_b32_e32 v40, 11, v18
	s_waitcnt lgkmcnt(0)
	v_cvt_pk_bf16_f32 v37, v16, v17
	ds_read2_b32 v[16:17], v29 offset0:8 offset1:41
	v_lshl_add_u64 v[40:41], v[42:43], 0, v[40:41]
	v_mov_b32_e32 v194, s98
	v_sub_u32_e32 v190, v40, v194
	v_bfe_u32 v191, v190, 19, 1
	v_bfe_u32 v192, v190, 17, 1
	v_bfe_u32 v193, v190, 16, 1
	v_and_b32_e32 v190, 0xfff4ffff, v190
	v_lshl_or_b32 v190, v192, 19, v190
	v_lshl_or_b32 v190, v193, 17, v190
	v_lshl_or_b32 v190, v191, 16, v190
	v_mov_b32_e32 v195, 0
	v_mov_b32_e32 v196, v190
	v_mov_b32_e32 v197, 0
	v_lshl_add_u64 v[196:197], v[196:197], 0, s[98:99]
	global_store_dwordx4 v[196:197], v[34:37], off
	v_or_b32_e32 v18, s37, v21
	v_lshlrev_b32_e32 v44, 11, v18
	s_waitcnt lgkmcnt(0)
	v_cvt_pk_bf16_f32 v34, v16, v17
	ds_read2_b32 v[16:17], v29 offset0:74 offset1:107
	s_waitcnt lgkmcnt(0)
	v_cvt_pk_bf16_f32 v35, v16, v17
	ds_read2_b32 v[16:17], v29 offset0:140 offset1:173
	s_waitcnt lgkmcnt(0)
	v_cvt_pk_bf16_f32 v36, v16, v17
	ds_read2_b32 v[16:17], v29 offset0:206 offset1:239
	v_or_b32_e32 v18, s7, v30
	s_waitcnt lgkmcnt(0)
	v_cvt_pk_bf16_f32 v37, v16, v17
	ds_read2_b32 v[16:17], v29 offset0:16 offset1:49
	v_lshl_add_u64 v[44:45], v[42:43], 0, v[44:45]
	v_or_b32_e32 v18, s36, v18
	v_mov_b32_e32 v194, s98
	v_sub_u32_e32 v190, v44, v194
	v_bfe_u32 v191, v190, 19, 1
	v_bfe_u32 v192, v190, 17, 1
	v_bfe_u32 v193, v190, 16, 1
	v_and_b32_e32 v190, 0xfff4ffff, v190
	v_lshl_or_b32 v190, v192, 19, v190
	v_lshl_or_b32 v190, v193, 17, v190
	v_lshl_or_b32 v190, v191, 16, v190
	v_mov_b32_e32 v195, 0
	v_mov_b32_e32 v196, v190
	v_mov_b32_e32 v197, 0
	v_lshl_add_u64 v[196:197], v[196:197], 0, s[98:99]
	global_store_dwordx4 v[196:197], v[34:37], off
	v_add_co_u32_e32 v40, vcc, s33, v40
	s_waitcnt lgkmcnt(0)
	v_cvt_pk_bf16_f32 v34, v16, v17
	ds_read2_b32 v[16:17], v29 offset0:82 offset1:115
	v_or_b32_e32 v18, s6, v18
	s_waitcnt lgkmcnt(0)
	v_cvt_pk_bf16_f32 v35, v16, v17
	ds_read2_b32 v[16:17], v29 offset0:148 offset1:181
	v_addc_co_u32_e32 v41, vcc, 0, v41, vcc
	v_or_b32_e32 v18, s10, v18
	s_waitcnt lgkmcnt(0)
	v_cvt_pk_bf16_f32 v36, v16, v17
	ds_read2_b32 v[16:17], v29 offset0:214 offset1:247
	s_waitcnt lgkmcnt(0)
	v_cvt_pk_bf16_f32 v37, v16, v17
	v_mov_b32_e32 v194, s98
	v_sub_u32_e32 v190, v40, v194
	v_bfe_u32 v191, v190, 19, 1
	v_bfe_u32 v192, v190, 17, 1
	v_bfe_u32 v193, v190, 16, 1
	v_and_b32_e32 v190, 0xfff4ffff, v190
	v_lshl_or_b32 v190, v192, 19, v190
	v_lshl_or_b32 v190, v193, 17, v190
	v_lshl_or_b32 v190, v191, 16, v190
	v_mov_b32_e32 v195, 0
	v_mov_b32_e32 v196, v190
	v_mov_b32_e32 v197, 0
	v_lshl_add_u64 v[196:197], v[196:197], 0, s[98:99]
	global_store_dwordx4 v[196:197], v[34:37], off
	v_mov_b32_e32 v41, v1
	v_lshlrev_b32_e32 v40, 11, v18
	ds_read2_b32 v[16:17], v29 offset0:24 offset1:57
	v_lshl_add_u64 v[40:41], v[42:43], 0, v[40:41]
	s_waitcnt lgkmcnt(0)
	v_cvt_pk_bf16_f32 v34, v16, v17
	ds_read2_b32 v[16:17], v29 offset0:90 offset1:123
	v_add_co_u32_e32 v40, vcc, 0x80000, v40
	s_waitcnt lgkmcnt(0)
	v_cvt_pk_bf16_f32 v35, v16, v17
	ds_read2_b32 v[16:17], v29 offset0:156 offset1:189
	v_addc_co_u32_e32 v41, vcc, 0, v41, vcc
	s_waitcnt lgkmcnt(0)
	v_cvt_pk_bf16_f32 v36, v16, v17
	ds_read2_b32 v[16:17], v29 offset0:222 offset1:255
	s_waitcnt lgkmcnt(0)
	v_cvt_pk_bf16_f32 v37, v16, v17
	v_mov_b32_e32 v194, s98
	v_sub_u32_e32 v190, v40, v194
	v_bfe_u32 v191, v190, 19, 1
	v_bfe_u32 v192, v190, 17, 1
	v_bfe_u32 v193, v190, 16, 1
	v_and_b32_e32 v190, 0xfff4ffff, v190
	v_lshl_or_b32 v190, v192, 19, v190
	v_lshl_or_b32 v190, v193, 17, v190
	v_lshl_or_b32 v190, v191, 16, v190
	v_mov_b32_e32 v195, 0
	v_mov_b32_e32 v196, v190
	v_mov_b32_e32 v197, 0
	v_lshl_add_u64 v[196:197], v[196:197], 0, s[98:99]
	global_store_dwordx4 v[196:197], v[34:37], off
	s_waitcnt lgkmcnt(0)
	s_and_b32 s36, s2, 0xfffffe00
	s_cmpk_lt_i32 s36, 0xa00
	s_mov_b64 s[6:7], -1
	s_cbranch_scc0 .LBB0_2598
